# v14 + s_sleep throttle in the B-layer weight-conversion loops that run beside the input GEMM's partial last round (less memory interference with the critical GEMM workgroups)
# baseline (speedup 1.0000x reference)
.LBB0_551:
	s_sleep 100
	s_mul_hi_i32 s4, s24, 0x66666667
	s_lshr_b32 s18, s4, 31
	s_ashr_i32 s4, s4, 5
	s_add_i32 s4, s4, s18
	s_lshl_b32 s20, s4, 6
	s_mulk_i32 s4, 0xf600
	s_add_i32 s18, s22, s4
	v_or_b32_e32 v6, s20, v10
	v_mov_b64_e32 v[8:9], s[8:9]
	s_movk_i32 s4, 0x2800
	v_mad_i64_i32 v[8:9], s[26:27], v6, s4, v[8:9]
	s_ashr_i32 s19, s18, 31
	v_ashrrev_i32_e32 v7, 31, v6
	v_lshl_add_u64 v[8:9], s[18:19], 2, v[8:9]
	v_lshl_add_u64 v[8:9], v[8:9], 0, v[176:177]
	v_lshl_add_u64 v[38:39], v[6:7], 2, s[10:11]
	global_load_dword v16, v[8:9], off nt
	global_load_dword v6, v[38:39], off
	global_load_dword v7, v[38:39], off offset:232
	s_movk_i32 s4, 0x5000
	v_add_co_u32_e32 v14, vcc, s4, v8
	s_mov_b32 s4, 0xa000
	s_nop 0
	v_addc_co_u32_e32 v15, vcc, 0, v9, vcc
	global_load_dword v17, v[14:15], off nt
	v_add_co_u32_e32 v14, vcc, s4, v8
	s_mov_b32 s4, 0xf000
	s_nop 0
	v_addc_co_u32_e32 v15, vcc, 0, v9, vcc
	global_load_dword v18, v[14:15], off nt
	v_add_co_u32_e32 v14, vcc, s4, v8
	s_mov_b32 s4, 0x19000
	s_nop 0
	v_addc_co_u32_e32 v15, vcc, 0, v9, vcc
	global_load_dword v19, v[14:15], off nt
	v_add_co_u32_e32 v14, vcc, s51, v8
	s_ashr_i32 s21, s20, 31
	s_nop 0
	v_addc_co_u32_e32 v15, vcc, 0, v9, vcc
	global_load_dword v20, v[14:15], off nt
	v_add_co_u32_e32 v14, vcc, s4, v8
	s_mov_b32 s4, 0x23000
	s_nop 0
	v_addc_co_u32_e32 v15, vcc, 0, v9, vcc
	global_load_dword v21, v[14:15], off nt
	v_add_co_u32_e32 v14, vcc, s55, v8
	s_add_i32 s24, s24, s66
	s_nop 0
	v_addc_co_u32_e32 v15, vcc, 0, v9, vcc
	global_load_dword v22, v[14:15], off nt
	v_add_co_u32_e32 v14, vcc, s4, v8
	s_mov_b32 s4, 0x2d000
	s_nop 0
	v_addc_co_u32_e32 v15, vcc, 0, v9, vcc
	global_load_dword v23, v[14:15], off nt
	v_add_co_u32_e32 v14, vcc, s37, v8
	s_add_i32 s22, s22, s23
	s_nop 0
	v_addc_co_u32_e32 v15, vcc, 0, v9, vcc
	global_load_dword v24, v[14:15], off nt
	v_add_co_u32_e32 v14, vcc, s4, v8
	s_mov_b32 s4, 0x32000
	s_nop 0
	v_addc_co_u32_e32 v15, vcc, 0, v9, vcc
	global_load_dword v25, v[14:15], off nt
	v_add_co_u32_e32 v14, vcc, s4, v8
	s_mov_b32 s4, 0x37000
	s_nop 0
	v_addc_co_u32_e32 v15, vcc, 0, v9, vcc
	global_load_dword v26, v[14:15], off nt
	v_add_co_u32_e32 v14, vcc, s4, v8
	s_mov_b32 s4, 0x41000
	s_nop 0
	v_addc_co_u32_e32 v15, vcc, 0, v9, vcc
	global_load_dword v27, v[14:15], off nt
	v_add_co_u32_e32 v14, vcc, s54, v8
	s_cmpk_lt_i32 s24, 0xa00
	s_nop 0
	v_addc_co_u32_e32 v15, vcc, 0, v9, vcc
	global_load_dword v29, v[14:15], off nt
	v_add_co_u32_e32 v14, vcc, s4, v8
	s_mov_b32 s4, 0x46000
	s_nop 0
	v_addc_co_u32_e32 v15, vcc, 0, v9, vcc
	s_waitcnt vmcnt(0)
	v_mul_f32_e32 v59, v16, v6
	global_load_dword v6, v[38:39], off offset:8
	global_load_dword v31, v[14:15], off nt
	v_add_co_u32_e32 v14, vcc, s4, v8
	s_mov_b32 s4, 0x4b000
	s_nop 0
	v_addc_co_u32_e32 v15, vcc, 0, v9, vcc
	global_load_dword v40, v[14:15], off nt
	v_add_co_u32_e32 v14, vcc, s4, v8
	s_mov_b32 s4, 0x55000
	s_nop 0
	v_addc_co_u32_e32 v15, vcc, 0, v9, vcc
	global_load_dword v41, v[14:15], off nt
	v_add_co_u32_e32 v14, vcc, s38, v8
	s_nop 1
	v_addc_co_u32_e32 v15, vcc, 0, v9, vcc
	global_load_dword v44, v[14:15], off nt
	v_add_co_u32_e32 v14, vcc, s4, v8
	s_mov_b32 s4, 0x5f000
	s_nop 0
	v_addc_co_u32_e32 v15, vcc, 0, v9, vcc
	global_load_dword v45, v[14:15], off nt
	v_add_co_u32_e32 v14, vcc, s81, v8
	s_nop 1
	v_addc_co_u32_e32 v15, vcc, 0, v9, vcc
	global_load_dword v46, v[14:15], off nt
	v_add_co_u32_e32 v14, vcc, s4, v8
	s_mov_b32 s4, 0x69000
	s_nop 0
	v_addc_co_u32_e32 v15, vcc, 0, v9, vcc
	global_load_dword v47, v[14:15], off nt
	v_add_co_u32_e32 v14, vcc, s83, v8
	s_nop 1
	v_addc_co_u32_e32 v15, vcc, 0, v9, vcc
	global_load_dword v48, v[14:15], off nt
	v_add_co_u32_e32 v14, vcc, s4, v8
	s_mov_b32 s4, 0x6e000
	s_nop 0
	v_addc_co_u32_e32 v15, vcc, 0, v9, vcc
	global_load_dword v49, v[14:15], off nt
	v_add_co_u32_e32 v14, vcc, s4, v8
	s_mov_b32 s4, 0x73000
	s_nop 0
	v_addc_co_u32_e32 v15, vcc, 0, v9, vcc
	global_load_dword v50, v[14:15], off nt
	v_add_co_u32_e32 v14, vcc, s4, v8
	s_mov_b32 s4, 0x7d000
	s_nop 0
	v_addc_co_u32_e32 v15, vcc, 0, v9, vcc
	global_load_dword v51, v[14:15], off nt
	v_add_co_u32_e32 v14, vcc, s43, v8
	s_nop 1
	v_addc_co_u32_e32 v15, vcc, 0, v9, vcc
	global_load_dword v52, v[14:15], off nt
	v_add_co_u32_e32 v14, vcc, s4, v8
	s_mov_b32 s4, 0x82000
	s_nop 0
	v_addc_co_u32_e32 v15, vcc, 0, v9, vcc
	global_load_dword v53, v[14:15], off nt
	v_add_co_u32_e32 v14, vcc, s4, v8
	s_mov_b32 s4, 0x87000
	s_nop 0
	v_addc_co_u32_e32 v15, vcc, 0, v9, vcc
	global_load_dword v54, v[14:15], off nt
	v_add_co_u32_e32 v14, vcc, s4, v8
	s_mov_b32 s4, 0x8c000
	s_nop 0
	v_addc_co_u32_e32 v15, vcc, 0, v9, vcc
	global_load_dword v55, v[14:15], off nt
	v_add_co_u32_e32 v14, vcc, s4, v8
	s_mov_b32 s4, 0x91000
	s_nop 0
	v_addc_co_u32_e32 v15, vcc, 0, v9, vcc
	global_load_dword v56, v[14:15], off nt
	v_add_co_u32_e32 v14, vcc, s4, v8
	s_mov_b32 s4, 0x9b000
	s_nop 0
	v_addc_co_u32_e32 v15, vcc, 0, v9, vcc
	global_load_dword v57, v[14:15], off nt
	v_add_co_u32_e32 v14, vcc, s84, v8
	s_waitcnt vmcnt(0)
	v_mul_f32_e32 v7, v57, v7
	v_addc_co_u32_e32 v15, vcc, 0, v9, vcc
	v_add_co_u32_e32 v8, vcc, s4, v8
	global_load_dword v15, v[14:15], off nt
	s_nop 0
	v_addc_co_u32_e32 v9, vcc, 0, v9, vcc
	global_load_dword v58, v[8:9], off nt
	s_nop 0
	global_load_dword v9, v[38:39], off offset:240
	v_mul_f32_e32 v60, v17, v6
	global_load_dword v6, v[38:39], off offset:16
	s_waitcnt vmcnt(1)
	v_mul_f32_e32 v9, v15, v9
	global_load_dword v15, v[38:39], off offset:248
	s_waitcnt vmcnt(1)
	v_mul_f32_e32 v61, v18, v6
	global_load_dword v6, v[38:39], off offset:24
	s_waitcnt vmcnt(1)
	v_mul_f32_e32 v15, v58, v15
	s_waitcnt vmcnt(0)
	v_mul_f32_e32 v62, v19, v6
	global_load_dword v6, v[38:39], off offset:32
	s_waitcnt vmcnt(0)
	v_mul_f32_e32 v32, v20, v6
	global_load_dword v6, v[38:39], off offset:40
	s_waitcnt vmcnt(0)
	v_mul_f32_e32 v34, v21, v6
	global_load_dword v6, v[38:39], off offset:48
	s_waitcnt vmcnt(0)
	v_mul_f32_e32 v36, v22, v6
	global_load_dword v6, v[38:39], off offset:56
	s_waitcnt vmcnt(0)
	v_mul_f32_e32 v37, v23, v6
	global_load_dword v6, v[38:39], off offset:64
	s_waitcnt vmcnt(0)
	v_mul_f32_e32 v28, v24, v6
	global_load_dword v6, v[38:39], off offset:72
	s_waitcnt vmcnt(0)
	v_mul_f32_e32 v30, v25, v6
	global_load_dword v6, v[38:39], off offset:80
	s_waitcnt vmcnt(0)
	v_mul_f32_e32 v33, v26, v6
	global_load_dword v6, v[38:39], off offset:88
	s_waitcnt vmcnt(0)
	v_mul_f32_e32 v35, v27, v6
	global_load_dword v6, v[38:39], off offset:96
	s_waitcnt vmcnt(0)
	v_mul_f32_e32 v26, v29, v6
	global_load_dword v6, v[38:39], off offset:104
	s_waitcnt vmcnt(0)
	v_mul_f32_e32 v27, v31, v6
	global_load_dword v6, v[38:39], off offset:112
	s_waitcnt vmcnt(0)
	v_mul_f32_e32 v29, v40, v6
	global_load_dword v6, v[38:39], off offset:120
	s_waitcnt vmcnt(0)
	v_mul_f32_e32 v31, v41, v6
	global_load_dword v6, v[38:39], off offset:128
	s_waitcnt vmcnt(0)
	v_mul_f32_e32 v20, v44, v6
	global_load_dword v6, v[38:39], off offset:136
	s_waitcnt vmcnt(0)
	v_mul_f32_e32 v22, v45, v6
	global_load_dword v6, v[38:39], off offset:144
	s_waitcnt vmcnt(0)
	v_mul_f32_e32 v24, v46, v6
	global_load_dword v6, v[38:39], off offset:152
	s_waitcnt vmcnt(0)
	v_mul_f32_e32 v25, v47, v6
	global_load_dword v6, v[38:39], off offset:160
	s_waitcnt vmcnt(0)
	v_mul_f32_e32 v16, v48, v6
	global_load_dword v6, v[38:39], off offset:168
	s_waitcnt vmcnt(0)
	v_mul_f32_e32 v18, v49, v6
	global_load_dword v6, v[38:39], off offset:176
	s_waitcnt vmcnt(0)
	v_mul_f32_e32 v21, v50, v6
	global_load_dword v6, v[38:39], off offset:184
	s_waitcnt vmcnt(0)
	v_mul_f32_e32 v23, v51, v6
	global_load_dword v6, v[38:39], off offset:192
	s_waitcnt vmcnt(0)
	v_mul_f32_e32 v8, v52, v6
	global_load_dword v6, v[38:39], off offset:200
	s_waitcnt vmcnt(0)
	v_mul_f32_e32 v14, v53, v6
	global_load_dword v6, v[38:39], off offset:208
	s_waitcnt vmcnt(0)
	v_mul_f32_e32 v17, v54, v6
	global_load_dword v6, v[38:39], off offset:216
	s_waitcnt vmcnt(0)
	v_mul_f32_e32 v19, v55, v6
	global_load_dword v6, v[38:39], off offset:224
	v_add_u32_e32 v38, 0x400, v13
	ds_write2_b32 v13, v59, v60 offset1:66
	ds_write2_b32 v13, v61, v62 offset0:132 offset1:198
	ds_write2_b32 v38, v32, v34 offset0:8 offset1:74
	ds_write2_b32 v38, v36, v37 offset0:140 offset1:206
	v_add_u32_e32 v32, 0x800, v13
	ds_write2_b32 v32, v28, v30 offset0:16 offset1:82
	ds_write2_b32 v32, v33, v35 offset0:148 offset1:214
	v_add_u32_e32 v28, 0xc00, v13
	ds_write2_b32 v28, v26, v27 offset0:24 offset1:90
	ds_write2_b32 v28, v29, v31 offset0:156 offset1:222
	v_add_u32_e32 v26, 0x1000, v13
	ds_write2_b32 v26, v20, v22 offset0:32 offset1:98
	ds_write2_b32 v26, v24, v25 offset0:164 offset1:230
	v_add_u32_e32 v20, 0x1400, v13
	ds_write2_b32 v20, v16, v18 offset0:40 offset1:106
	ds_write2_b32 v20, v21, v23 offset0:172 offset1:238
	v_add_u32_e32 v16, 0x1800, v13
	ds_write2_b32 v16, v8, v14 offset0:48 offset1:114
	ds_write2_b32 v16, v17, v19 offset0:180 offset1:246
	v_add_u32_e32 v8, 0x1c00, v13
	s_waitcnt vmcnt(0)
	v_mul_f32_e32 v6, v56, v6
	ds_write2_b32 v8, v6, v7 offset0:56 offset1:122
	ds_write2_b32 v8, v9, v15 offset0:188 offset1:254
	s_waitcnt lgkmcnt(0)
	ds_read2_b32 v[8:9], v12 offset1:33
	s_waitcnt lgkmcnt(0)
	v_cvt_pk_bf16_f32 v14, v8, v9
	ds_read2_b32 v[8:9], v12 offset0:66 offset1:99
	s_waitcnt lgkmcnt(0)
	v_cvt_pk_bf16_f32 v15, v8, v9
	ds_read2_b32 v[8:9], v12 offset0:132 offset1:165
	s_waitcnt lgkmcnt(0)
	v_cvt_pk_bf16_f32 v16, v8, v9
	ds_read2_b32 v[8:9], v12 offset0:198 offset1:231
	s_waitcnt lgkmcnt(0)
	v_cvt_pk_bf16_f32 v17, v8, v9
	v_add_u32_e32 v8, s18, v11
	v_ashrrev_i32_e32 v9, 31, v8
	v_lshl_add_u64 v[6:7], s[20:21], 1, v[4:5]
	v_lshlrev_b64 v[18:19], 12, v[8:9]
	v_lshl_add_u64 v[18:19], v[6:7], 0, v[18:19]
	global_store_dwordx4 v[18:19], v[14:17], off
	ds_read2_b32 v[14:15], v12 offset0:8 offset1:41
	s_waitcnt lgkmcnt(0)
	v_cvt_pk_bf16_f32 v14, v14, v15
	ds_read2_b32 v[16:17], v12 offset0:74 offset1:107
	s_waitcnt lgkmcnt(0)
	v_cvt_pk_bf16_f32 v15, v16, v17
	ds_read2_b32 v[16:17], v12 offset0:140 offset1:173
	s_waitcnt lgkmcnt(0)
	v_cvt_pk_bf16_f32 v16, v16, v17
	ds_read2_b32 v[18:19], v12 offset0:206 offset1:239
	s_waitcnt lgkmcnt(0)
	v_cvt_pk_bf16_f32 v17, v18, v19
	v_add_u32_e32 v18, 8, v8
	v_ashrrev_i32_e32 v19, 31, v18
	v_lshlrev_b64 v[18:19], 12, v[18:19]
	v_lshl_add_u64 v[18:19], v[6:7], 0, v[18:19]
	global_store_dwordx4 v[18:19], v[14:17], off
	ds_read2_b32 v[14:15], v12 offset0:16 offset1:49
	s_waitcnt lgkmcnt(0)
	v_cvt_pk_bf16_f32 v14, v14, v15
	ds_read2_b32 v[16:17], v12 offset0:82 offset1:115
	s_waitcnt lgkmcnt(0)
	v_cvt_pk_bf16_f32 v15, v16, v17
	ds_read2_b32 v[16:17], v12 offset0:148 offset1:181
	s_waitcnt lgkmcnt(0)
	v_cvt_pk_bf16_f32 v16, v16, v17
	ds_read2_b32 v[18:19], v12 offset0:214 offset1:247
	s_waitcnt lgkmcnt(0)
	v_cvt_pk_bf16_f32 v17, v18, v19
	v_add_u32_e32 v18, 16, v8
	v_ashrrev_i32_e32 v19, 31, v18
	v_lshlrev_b64 v[18:19], 12, v[18:19]
	v_lshl_add_u64 v[18:19], v[6:7], 0, v[18:19]
	v_add_u32_e32 v8, 24, v8
	global_store_dwordx4 v[18:19], v[14:17], off
	ds_read2_b32 v[14:15], v12 offset0:24 offset1:57
	v_ashrrev_i32_e32 v9, 31, v8
	s_waitcnt lgkmcnt(0)
	v_cvt_pk_bf16_f32 v14, v14, v15
	ds_read2_b32 v[16:17], v12 offset0:90 offset1:123
	v_lshlrev_b64 v[8:9], 12, v[8:9]
	s_waitcnt lgkmcnt(0)
	v_cvt_pk_bf16_f32 v15, v16, v17
	ds_read2_b32 v[16:17], v12 offset0:156 offset1:189
	v_lshl_add_u64 v[6:7], v[6:7], 0, v[8:9]
	s_waitcnt lgkmcnt(0)
	v_cvt_pk_bf16_f32 v16, v16, v17
	ds_read2_b32 v[18:19], v12 offset0:222 offset1:255
	s_waitcnt lgkmcnt(0)
	v_cvt_pk_bf16_f32 v17, v18, v19
	global_store_dwordx4 v[6:7], v[14:17], off
	s_waitcnt lgkmcnt(0)
	s_cbranch_scc1 .LBB0_551

.LBB0_557:
	s_sleep 100
	s_ashr_i32 s20, s23, 31
	s_lshr_b32 s20, s20, 25
	s_add_i32 s20, s23, s20
	s_ashr_i32 s21, s20, 7
	s_lshl_b32 s20, s21, 6
	v_or_b32_e32 v30, s20, v43
	s_lshl_b32 s21, s21, 12
	v_ashrrev_i32_e32 v31, 31, v30
	s_sub_i32 s24, s4, s21
	v_lshlrev_b64 v[6:7], 14, v[30:31]
	v_lshl_add_u64 v[6:7], s[10:11], 0, v[6:7]
	s_ashr_i32 s25, s24, 31
	v_lshl_add_u64 v[6:7], s[24:25], 2, v[6:7]
	v_lshlrev_b32_e32 v176, 2, v2
	v_lshl_add_u64 v[38:39], v[6:7], 0, v[176:177]
	v_add_co_u32_e32 v8, vcc, s52, v38
	global_load_dword v6, v[38:39], off nt
	s_nop 0
	v_addc_co_u32_e32 v9, vcc, 0, v39, vcc
	global_load_dword v7, v[8:9], off nt
	v_add_co_u32_e32 v8, vcc, s49, v38
	s_mov_b32 s24, 0x80000
	s_nop 0
	v_addc_co_u32_e32 v9, vcc, 0, v39, vcc
	v_add_co_u32_e32 v10, vcc, s61, v38
	global_load_dword v8, v[8:9], off nt
	s_nop 0
	v_addc_co_u32_e32 v11, vcc, 0, v39, vcc
	global_load_dword v9, v[10:11], off nt
	v_add_co_u32_e32 v10, vcc, s85, v38
	s_nop 1
	v_addc_co_u32_e32 v11, vcc, 0, v39, vcc
	v_add_co_u32_e32 v12, vcc, s37, v38
	global_load_dword v10, v[10:11], off nt
	s_nop 0
	v_addc_co_u32_e32 v13, vcc, 0, v39, vcc
	global_load_dword v11, v[12:13], off nt
	v_add_co_u32_e32 v12, vcc, s50, v38
	s_nop 1
	v_addc_co_u32_e32 v13, vcc, 0, v39, vcc
	v_add_co_u32_e32 v14, vcc, s89, v38
	global_load_dword v12, v[12:13], off nt
	s_nop 0
	v_addc_co_u32_e32 v15, vcc, 0, v39, vcc
	global_load_dword v13, v[14:15], off nt
	v_add_co_u32_e32 v14, vcc, s33, v38
	s_nop 1
	v_addc_co_u32_e32 v15, vcc, 0, v39, vcc
	v_add_co_u32_e32 v16, vcc, s53, v38
	global_load_dword v14, v[14:15], off nt
	s_nop 0
	v_addc_co_u32_e32 v17, vcc, 0, v39, vcc
	global_load_dword v15, v[16:17], off nt
	v_add_co_u32_e32 v16, vcc, s38, v38
	s_nop 1
	v_addc_co_u32_e32 v17, vcc, 0, v39, vcc
	v_add_co_u32_e32 v18, vcc, s34, v38
	global_load_dword v16, v[16:17], off nt
	s_nop 0
	v_addc_co_u32_e32 v19, vcc, 0, v39, vcc
	global_load_dword v17, v[18:19], off nt
	v_add_co_u32_e32 v18, vcc, s57, v38
	s_nop 1
	v_addc_co_u32_e32 v19, vcc, 0, v39, vcc
	v_add_co_u32_e32 v20, vcc, s39, v38
	global_load_dword v18, v[18:19], off nt
	s_nop 0
	v_addc_co_u32_e32 v21, vcc, 0, v39, vcc
	global_load_dword v19, v[20:21], off nt
	v_add_co_u32_e32 v20, vcc, s42, v38
	s_nop 1
	v_addc_co_u32_e32 v21, vcc, 0, v39, vcc
	v_add_co_u32_e32 v22, vcc, s43, v38
	global_load_dword v20, v[20:21], off nt
	s_nop 0
	v_addc_co_u32_e32 v23, vcc, 0, v39, vcc
	global_load_dword v21, v[22:23], off nt
	v_add_co_u32_e32 v22, vcc, s24, v38
	s_mov_b32 s24, 0x88000
	s_nop 0
	v_addc_co_u32_e32 v23, vcc, 0, v39, vcc
	v_add_co_u32_e32 v24, vcc, s24, v38
	global_load_dword v22, v[22:23], off nt
	s_nop 0
	v_addc_co_u32_e32 v25, vcc, 0, v39, vcc
	global_load_dword v23, v[24:25], off nt
	v_add_co_u32_e32 v24, vcc, s48, v38
	s_mov_b32 s24, 0x98000
	s_nop 0
	v_addc_co_u32_e32 v25, vcc, 0, v39, vcc
	v_add_co_u32_e32 v26, vcc, s24, v38
	s_mov_b32 s24, 0xa0000
	s_nop 0
	v_addc_co_u32_e32 v27, vcc, 0, v39, vcc
	global_load_dword v24, v[24:25], off nt
	s_nop 0
	global_load_dword v25, v[26:27], off nt
	v_add_co_u32_e32 v26, vcc, s24, v38
	s_mov_b32 s24, 0xb0000
	s_nop 0
	v_addc_co_u32_e32 v27, vcc, 0, v39, vcc
	v_add_co_u32_e32 v28, vcc, s5, v38
	global_load_dword v26, v[26:27], off nt
	s_nop 0
	v_addc_co_u32_e32 v29, vcc, 0, v39, vcc
	global_load_dword v27, v[28:29], off nt
	v_add_co_u32_e32 v28, vcc, s24, v38
	s_mov_b32 s24, 0xb8000
	s_nop 0
	v_addc_co_u32_e32 v29, vcc, 0, v39, vcc
	v_add_co_u32_e32 v32, vcc, s24, v38
	s_mov_b32 s24, 0xc0000
	s_nop 0
	v_addc_co_u32_e32 v33, vcc, 0, v39, vcc
	global_load_dword v28, v[28:29], off nt
	s_nop 0
	global_load_dword v29, v[32:33], off nt
	v_add_co_u32_e32 v32, vcc, s24, v38
	s_mov_b32 s24, 0xc8000
	s_nop 0
	v_addc_co_u32_e32 v33, vcc, 0, v39, vcc
	v_add_co_u32_e32 v34, vcc, s24, v38
	s_mov_b32 s24, 0xd0000
	s_nop 0
	v_addc_co_u32_e32 v35, vcc, 0, v39, vcc
	global_load_dword v32, v[32:33], off nt
	s_nop 0
	global_load_dword v33, v[34:35], off nt
	v_add_co_u32_e32 v34, vcc, s24, v38
	s_mov_b32 s24, 0xd8000
	s_nop 0
	v_addc_co_u32_e32 v35, vcc, 0, v39, vcc
	v_add_co_u32_e32 v36, vcc, s24, v38
	s_mov_b32 s24, 0xe0000
	s_nop 0
	v_addc_co_u32_e32 v37, vcc, 0, v39, vcc
	global_load_dword v34, v[34:35], off nt
	s_nop 0
	global_load_dword v35, v[36:37], off nt
	v_add_co_u32_e32 v36, vcc, s24, v38
	s_nop 1
	v_addc_co_u32_e32 v37, vcc, 0, v39, vcc
	v_add_co_u32_e32 v40, vcc, 0xe8000, v38
	global_load_dword v36, v[36:37], off nt
	s_nop 0
	v_addc_co_u32_e32 v41, vcc, 0, v39, vcc
	global_load_dword v37, v[40:41], off nt
	v_add_co_u32_e32 v40, vcc, 0xf0000, v38
	s_nop 1
	v_addc_co_u32_e32 v41, vcc, 0, v39, vcc
	v_add_co_u32_e32 v38, vcc, 0xf8000, v38
	global_load_dword v40, v[40:41], off nt
	s_nop 0
	v_addc_co_u32_e32 v39, vcc, 0, v39, vcc
	global_load_dword v41, v[38:39], off nt
	s_andn2_b64 vcc, exec, s[18:19]
	s_cbranch_vccnz .LBB0_556
	v_lshl_add_u64 v[30:31], v[30:31], 2, s[8:9]
	global_load_dword v38, v[30:31], off
	global_load_dword v39, v[30:31], off offset:8
	global_load_dword v52, v[30:31], off offset:16
	global_load_dword v53, v[30:31], off offset:24
	global_load_dword v54, v[30:31], off offset:32
	global_load_dword v55, v[30:31], off offset:40
	global_load_dword v56, v[30:31], off offset:48
	global_load_dword v57, v[30:31], off offset:56
	global_load_dword v58, v[30:31], off offset:64
	global_load_dword v59, v[30:31], off offset:72
	global_load_dword v60, v[30:31], off offset:80
	global_load_dword v61, v[30:31], off offset:88
	global_load_dword v62, v[30:31], off offset:96
	global_load_dword v63, v[30:31], off offset:104
	global_load_dword v64, v[30:31], off offset:112
	global_load_dword v65, v[30:31], off offset:120
	global_load_dword v66, v[30:31], off offset:128
	global_load_dword v67, v[30:31], off offset:136
	global_load_dword v68, v[30:31], off offset:144
	global_load_dword v69, v[30:31], off offset:152
	global_load_dword v70, v[30:31], off offset:160
	global_load_dword v71, v[30:31], off offset:168
	global_load_dword v72, v[30:31], off offset:176
	global_load_dword v73, v[30:31], off offset:184
	global_load_dword v74, v[30:31], off offset:192
	global_load_dword v75, v[30:31], off offset:200
	global_load_dword v76, v[30:31], off offset:208
	global_load_dword v77, v[30:31], off offset:216
	global_load_dword v78, v[30:31], off offset:224
	global_load_dword v79, v[30:31], off offset:232
	global_load_dword v80, v[30:31], off offset:240
	global_load_dword v81, v[30:31], off offset:248
	s_waitcnt vmcnt(0)
	v_pk_mul_f32 v[6:7], v[6:7], v[38:39]
	v_pk_mul_f32 v[8:9], v[8:9], v[52:53]
	v_pk_mul_f32 v[10:11], v[10:11], v[54:55]
	v_pk_mul_f32 v[12:13], v[12:13], v[56:57]
	v_pk_mul_f32 v[14:15], v[14:15], v[58:59]
	v_pk_mul_f32 v[16:17], v[16:17], v[60:61]
	v_pk_mul_f32 v[18:19], v[18:19], v[62:63]
	v_pk_mul_f32 v[20:21], v[20:21], v[64:65]
	v_pk_mul_f32 v[22:23], v[22:23], v[66:67]
	v_pk_mul_f32 v[24:25], v[24:25], v[68:69]
	v_pk_mul_f32 v[26:27], v[26:27], v[70:71]
	v_pk_mul_f32 v[28:29], v[28:29], v[72:73]
	v_pk_mul_f32 v[32:33], v[32:33], v[74:75]
	v_pk_mul_f32 v[34:35], v[34:35], v[76:77]
	v_pk_mul_f32 v[36:37], v[36:37], v[78:79]
	v_pk_mul_f32 v[40:41], v[40:41], v[80:81]
	s_branch .LBB0_556

.LBB0_565:
	s_sleep 100
	s_mul_hi_i32 s30, s25, 0x2aaaaaab
	s_lshr_b32 s31, s30, 31
	s_ashr_i32 s30, s30, 4
	s_add_i32 s30, s30, s31
	s_lshl_b32 s44, s30, 6
	s_mulk_i32 s30, 0xf400
	s_add_i32 s30, s3, s30
	v_or_b32_e32 v30, s44, v48
	v_mov_b64_e32 v[6:7], s[26:27]
	s_movk_i32 s31, 0x3000
	v_mad_i64_i32 v[6:7], s[40:41], v30, s31, v[6:7]
	s_ashr_i32 s31, s30, 31
	v_lshl_add_u64 v[6:7], s[30:31], 2, v[6:7]
	v_lshl_add_u64 v[38:39], v[4:5], 2, v[6:7]
	s_movk_i32 s31, 0x6000
	v_add_co_u32_e32 v8, vcc, s31, v38
	global_load_dword v6, v[38:39], off nt
	s_nop 0
	v_addc_co_u32_e32 v9, vcc, 0, v39, vcc
	global_load_dword v7, v[8:9], off nt
	v_add_co_u32_e32 v8, vcc, s46, v38
	s_mov_b32 s31, 0x12000
	s_nop 0
	v_addc_co_u32_e32 v9, vcc, 0, v39, vcc
	v_add_co_u32_e32 v10, vcc, s31, v38
	global_load_dword v8, v[8:9], off nt
	s_nop 0
	v_addc_co_u32_e32 v11, vcc, 0, v39, vcc
	global_load_dword v9, v[10:11], off nt
	v_add_co_u32_e32 v10, vcc, s61, v38
	s_mov_b32 s31, 0x2a000
	s_nop 0
	v_addc_co_u32_e32 v11, vcc, 0, v39, vcc
	v_add_co_u32_e32 v12, vcc, s55, v38
	global_load_dword v10, v[10:11], off nt
	s_nop 0
	v_addc_co_u32_e32 v13, vcc, 0, v39, vcc
	global_load_dword v11, v[12:13], off nt
	v_add_co_u32_e32 v12, vcc, s67, v38
	s_nop 1
	v_addc_co_u32_e32 v13, vcc, 0, v39, vcc
	v_add_co_u32_e32 v14, vcc, s31, v38
	global_load_dword v12, v[12:13], off nt
	s_nop 0
	v_addc_co_u32_e32 v15, vcc, 0, v39, vcc
	global_load_dword v13, v[14:15], off nt
	v_add_co_u32_e32 v14, vcc, s50, v38
	s_mov_b32 s31, 0x36000
	s_nop 0
	v_addc_co_u32_e32 v15, vcc, 0, v39, vcc
	v_add_co_u32_e32 v16, vcc, s31, v38
	global_load_dword v14, v[14:15], off nt
	s_nop 0
	v_addc_co_u32_e32 v17, vcc, 0, v39, vcc
	global_load_dword v15, v[16:17], off nt
	v_add_co_u32_e32 v16, vcc, s54, v38
	s_mov_b32 s31, 0x42000
	s_nop 0
	v_addc_co_u32_e32 v17, vcc, 0, v39, vcc
	v_add_co_u32_e32 v18, vcc, s31, v38
	global_load_dword v16, v[16:17], off nt
	s_nop 0
	v_addc_co_u32_e32 v19, vcc, 0, v39, vcc
	global_load_dword v17, v[18:19], off nt
	v_add_co_u32_e32 v18, vcc, s53, v38
	s_mov_b32 s31, 0x4e000
	s_nop 0
	v_addc_co_u32_e32 v19, vcc, 0, v39, vcc
	v_add_co_u32_e32 v20, vcc, s31, v38
	global_load_dword v18, v[18:19], off nt
	s_nop 0
	v_addc_co_u32_e32 v21, vcc, 0, v39, vcc
	global_load_dword v19, v[20:21], off nt
	v_add_co_u32_e32 v20, vcc, s14, v38
	s_mov_b32 s31, 0x66000
	s_nop 0
	v_addc_co_u32_e32 v21, vcc, 0, v39, vcc
	v_add_co_u32_e32 v22, vcc, s81, v38
	global_load_dword v20, v[20:21], off nt
	s_nop 0
	v_addc_co_u32_e32 v23, vcc, 0, v39, vcc
	global_load_dword v21, v[22:23], off nt
	v_add_co_u32_e32 v22, vcc, s57, v38
	s_nop 1
	v_addc_co_u32_e32 v23, vcc, 0, v39, vcc
	v_add_co_u32_e32 v24, vcc, s31, v38
	global_load_dword v22, v[22:23], off nt
	s_nop 0
	v_addc_co_u32_e32 v25, vcc, 0, v39, vcc
	global_load_dword v23, v[24:25], off nt
	v_add_co_u32_e32 v24, vcc, s15, v38
	s_mov_b32 s31, 0x72000
	s_nop 0
	v_addc_co_u32_e32 v25, vcc, 0, v39, vcc
	v_add_co_u32_e32 v26, vcc, s31, v38
	global_load_dword v24, v[24:25], off nt
	s_nop 0
	v_addc_co_u32_e32 v27, vcc, 0, v39, vcc
	global_load_dword v25, v[26:27], off nt
	v_add_co_u32_e32 v26, vcc, s43, v38
	s_mov_b32 s31, 0x7e000
	s_nop 0
	v_addc_co_u32_e32 v27, vcc, 0, v39, vcc
	v_add_co_u32_e32 v28, vcc, s31, v38
	s_mov_b32 s31, 0x84000
	s_nop 0
	v_addc_co_u32_e32 v29, vcc, 0, v39, vcc
	global_load_dword v26, v[26:27], off nt
	s_nop 0
	global_load_dword v27, v[28:29], off nt
	v_add_co_u32_e32 v28, vcc, s31, v38
	s_mov_b32 s31, 0x8a000
	s_nop 0
	v_addc_co_u32_e32 v29, vcc, 0, v39, vcc
	v_add_co_u32_e32 v32, vcc, s31, v38
	global_load_dword v28, v[28:29], off nt
	s_nop 0
	v_addc_co_u32_e32 v33, vcc, 0, v39, vcc
	global_load_dword v29, v[32:33], off nt
	v_add_co_u32_e32 v32, vcc, s48, v38
	s_mov_b32 s31, 0x9c000
	s_nop 0
	v_addc_co_u32_e32 v33, vcc, 0, v39, vcc
	v_add_co_u32_e32 v34, vcc, s84, v38
	global_load_dword v32, v[32:33], off nt
	s_nop 0
	v_addc_co_u32_e32 v35, vcc, 0, v39, vcc
	global_load_dword v33, v[34:35], off nt
	v_add_co_u32_e32 v34, vcc, s31, v38
	s_mov_b32 s31, 0xa2000
	s_nop 0
	v_addc_co_u32_e32 v35, vcc, 0, v39, vcc
	v_add_co_u32_e32 v36, vcc, s31, v38
	global_load_dword v34, v[34:35], off nt
	s_nop 0
	v_addc_co_u32_e32 v37, vcc, 0, v39, vcc
	global_load_dword v35, v[36:37], off nt
	v_add_co_u32_e32 v36, vcc, s5, v38
	s_nop 1
	v_addc_co_u32_e32 v37, vcc, 0, v39, vcc
	v_add_co_u32_e32 v40, vcc, 0xae000, v38
	global_load_dword v36, v[36:37], off nt
	s_nop 0
	v_addc_co_u32_e32 v41, vcc, 0, v39, vcc
	global_load_dword v37, v[40:41], off nt
	v_add_co_u32_e32 v40, vcc, 0xb4000, v38
	s_nop 1
	v_addc_co_u32_e32 v41, vcc, 0, v39, vcc
	v_add_co_u32_e32 v38, vcc, 0xba000, v38
	global_load_dword v40, v[40:41], off nt
	s_nop 0
	v_addc_co_u32_e32 v39, vcc, 0, v39, vcc
	global_load_dword v41, v[38:39], off nt
	s_andn2_b64 vcc, exec, s[20:21]
	s_cbranch_vccnz .LBB0_564
	v_ashrrev_i32_e32 v31, 31, v30
	v_lshl_add_u64 v[30:31], v[30:31], 2, s[28:29]
	global_load_dword v38, v[30:31], off
	global_load_dword v39, v[30:31], off offset:8
	global_load_dword v54, v[30:31], off offset:16
	global_load_dword v55, v[30:31], off offset:24
	global_load_dword v56, v[30:31], off offset:32
	global_load_dword v57, v[30:31], off offset:40
	global_load_dword v58, v[30:31], off offset:48
	global_load_dword v59, v[30:31], off offset:56
	global_load_dword v60, v[30:31], off offset:64
	global_load_dword v61, v[30:31], off offset:72
	global_load_dword v62, v[30:31], off offset:80
	global_load_dword v63, v[30:31], off offset:88
	global_load_dword v64, v[30:31], off offset:96
	global_load_dword v65, v[30:31], off offset:104
	global_load_dword v66, v[30:31], off offset:112
	global_load_dword v67, v[30:31], off offset:120
	global_load_dword v68, v[30:31], off offset:128
	global_load_dword v69, v[30:31], off offset:136
	global_load_dword v70, v[30:31], off offset:144
	global_load_dword v71, v[30:31], off offset:152
	global_load_dword v72, v[30:31], off offset:160
	global_load_dword v73, v[30:31], off offset:168
	global_load_dword v74, v[30:31], off offset:176
	global_load_dword v75, v[30:31], off offset:184
	global_load_dword v76, v[30:31], off offset:192
	global_load_dword v77, v[30:31], off offset:200
	global_load_dword v78, v[30:31], off offset:208
	global_load_dword v79, v[30:31], off offset:216
	global_load_dword v80, v[30:31], off offset:224
	global_load_dword v81, v[30:31], off offset:232
	global_load_dword v82, v[30:31], off offset:240
	global_load_dword v83, v[30:31], off offset:248
	s_waitcnt vmcnt(0)
	v_pk_mul_f32 v[6:7], v[6:7], v[38:39]
	v_pk_mul_f32 v[8:9], v[8:9], v[54:55]
	v_pk_mul_f32 v[10:11], v[10:11], v[56:57]
	v_pk_mul_f32 v[12:13], v[12:13], v[58:59]
	v_pk_mul_f32 v[14:15], v[14:15], v[60:61]
	v_pk_mul_f32 v[16:17], v[16:17], v[62:63]
	v_pk_mul_f32 v[18:19], v[18:19], v[64:65]
	v_pk_mul_f32 v[20:21], v[20:21], v[66:67]
	v_pk_mul_f32 v[22:23], v[22:23], v[68:69]
	v_pk_mul_f32 v[24:25], v[24:25], v[70:71]
	v_pk_mul_f32 v[26:27], v[26:27], v[72:73]
	v_pk_mul_f32 v[28:29], v[28:29], v[74:75]
	v_pk_mul_f32 v[32:33], v[32:33], v[76:77]
	v_pk_mul_f32 v[34:35], v[34:35], v[78:79]
	v_pk_mul_f32 v[36:37], v[36:37], v[80:81]
	v_pk_mul_f32 v[40:41], v[40:41], v[82:83]
	s_branch .LBB0_564

.LBB0_569:
	s_sleep 100
	s_ashr_i32 s26, s30, 31
	s_lshr_b32 s26, s26, 26
	s_add_i32 s26, s30, s26
	s_and_b32 s28, s26, 0xffffffc0
	s_lshl_b32 s26, s26, 5
	v_or_b32_e32 v6, s28, v48
	s_and_b32 s26, s26, 0xfffff800
	v_ashrrev_i32_e32 v7, 31, v6
	s_sub_i32 s26, s3, s26
	v_lshlrev_b64 v[6:7], 13, v[6:7]
	v_lshl_add_u64 v[6:7], s[24:25], 0, v[6:7]
	s_ashr_i32 s27, s26, 31
	v_lshl_add_u64 v[6:7], s[26:27], 2, v[6:7]
	v_lshl_add_u64 v[6:7], v[4:5], 2, v[6:7]
	s_movk_i32 s27, 0x4000
	v_add_co_u32_e32 v10, vcc, s27, v6
	global_load_dword v8, v[6:7], off nt
	s_nop 0
	v_addc_co_u32_e32 v11, vcc, 0, v7, vcc
	v_add_co_u32_e32 v12, vcc, s52, v6
	global_load_dword v10, v[10:11], off nt
	s_nop 0
	v_addc_co_u32_e32 v13, vcc, 0, v7, vcc
	v_add_co_u32_e32 v14, vcc, s46, v6
	global_load_dword v12, v[12:13], off nt
	s_nop 0
	v_addc_co_u32_e32 v15, vcc, 0, v7, vcc
	v_add_co_u32_e32 v16, vcc, s49, v6
	global_load_dword v14, v[14:15], off nt
	s_nop 0
	v_addc_co_u32_e32 v17, vcc, 0, v7, vcc
	global_load_dword v9, v[16:17], off nt
	v_add_co_u32_e32 v16, vcc, s51, v6
	s_mov_b32 s27, 0x1c000
	s_nop 0
	v_addc_co_u32_e32 v17, vcc, 0, v7, vcc
	global_load_dword v11, v[16:17], off nt
	v_add_co_u32_e32 v16, vcc, s61, v6
	s_ashr_i32 s29, s28, 31
	s_nop 0
	v_addc_co_u32_e32 v17, vcc, 0, v7, vcc
	global_load_dword v13, v[16:17], off nt
	v_add_co_u32_e32 v16, vcc, s27, v6
	s_mov_b32 s27, 0x2c000
	s_nop 0
	v_addc_co_u32_e32 v17, vcc, 0, v7, vcc
	global_load_dword v18, v[16:17], off nt
	v_add_co_u32_e32 v16, vcc, s85, v6
	s_add_i32 s30, s30, s66
	s_nop 0
	v_addc_co_u32_e32 v17, vcc, 0, v7, vcc
	global_load_dword v15, v[16:17], off nt
	v_add_co_u32_e32 v16, vcc, s67, v6
	s_add_i32 s3, s3, s4
	s_nop 0
	v_addc_co_u32_e32 v17, vcc, 0, v7, vcc
	v_add_co_u32_e32 v20, vcc, s37, v6
	global_load_dword v16, v[16:17], off nt
	s_nop 0
	v_addc_co_u32_e32 v21, vcc, 0, v7, vcc
	global_load_dword v17, v[20:21], off nt
	v_add_co_u32_e32 v20, vcc, s27, v6
	s_mov_b32 s27, 0x34000
	s_nop 0
	v_addc_co_u32_e32 v21, vcc, 0, v7, vcc
	global_load_dword v22, v[20:21], off nt
	v_add_co_u32_e32 v20, vcc, s50, v6
	s_cmpk_lt_i32 s30, 0x800
	s_nop 0
	v_addc_co_u32_e32 v21, vcc, 0, v7, vcc
	global_load_dword v19, v[20:21], off nt
	v_add_co_u32_e32 v20, vcc, s27, v6
	s_mov_b32 s27, 0x44000
	s_nop 0
	v_addc_co_u32_e32 v21, vcc, 0, v7, vcc
	global_load_dword v23, v[20:21], off nt
	v_add_co_u32_e32 v20, vcc, s89, v6
	s_nop 1
	v_addc_co_u32_e32 v21, vcc, 0, v7, vcc
	global_load_dword v24, v[20:21], off nt
	v_add_co_u32_e32 v20, vcc, s54, v6
	s_nop 1
	v_addc_co_u32_e32 v21, vcc, 0, v7, vcc
	global_load_dword v25, v[20:21], off nt
	v_add_co_u32_e32 v20, vcc, s33, v6
	s_nop 1
	v_addc_co_u32_e32 v21, vcc, 0, v7, vcc
	global_load_dword v26, v[20:21], off nt
	v_add_co_u32_e32 v20, vcc, s27, v6
	s_mov_b32 s27, 0x4c000
	s_nop 0
	v_addc_co_u32_e32 v21, vcc, 0, v7, vcc
	global_load_dword v27, v[20:21], off nt
	v_add_co_u32_e32 v20, vcc, s53, v6
	s_nop 1
	v_addc_co_u32_e32 v21, vcc, 0, v7, vcc
	global_load_dword v28, v[20:21], off nt
	v_add_co_u32_e32 v20, vcc, s27, v6
	s_mov_b32 s27, 0x5c000
	s_nop 0
	v_addc_co_u32_e32 v21, vcc, 0, v7, vcc
	global_load_dword v29, v[20:21], off nt
	v_add_co_u32_e32 v20, vcc, s38, v6
	s_nop 1
	v_addc_co_u32_e32 v21, vcc, 0, v7, vcc
	global_load_dword v30, v[20:21], off nt
	v_add_co_u32_e32 v20, vcc, s14, v6
	s_nop 1
	v_addc_co_u32_e32 v21, vcc, 0, v7, vcc
	global_load_dword v31, v[20:21], off nt
	v_add_co_u32_e32 v20, vcc, s34, v6
	s_nop 1
	v_addc_co_u32_e32 v21, vcc, 0, v7, vcc
	global_load_dword v32, v[20:21], off nt
	v_add_co_u32_e32 v20, vcc, s27, v6
	s_mov_b32 s27, 0x74000
	s_nop 0
	v_addc_co_u32_e32 v21, vcc, 0, v7, vcc
	global_load_dword v33, v[20:21], off nt
	v_add_co_u32_e32 v20, vcc, s57, v6
	s_nop 1
	v_addc_co_u32_e32 v21, vcc, 0, v7, vcc
	global_load_dword v34, v[20:21], off nt
	v_add_co_u32_e32 v20, vcc, s83, v6
	s_nop 1
	v_addc_co_u32_e32 v21, vcc, 0, v7, vcc
	global_load_dword v35, v[20:21], off nt
	v_add_co_u32_e32 v20, vcc, s39, v6
	s_nop 1
	v_addc_co_u32_e32 v21, vcc, 0, v7, vcc
	global_load_dword v36, v[20:21], off nt
	v_add_co_u32_e32 v20, vcc, s15, v6
	s_nop 1
	v_addc_co_u32_e32 v21, vcc, 0, v7, vcc
	global_load_dword v37, v[20:21], off nt
	v_add_co_u32_e32 v20, vcc, s42, v6
	s_nop 1
	v_addc_co_u32_e32 v21, vcc, 0, v7, vcc
	global_load_dword v38, v[20:21], off nt
	v_add_co_u32_e32 v20, vcc, s27, v6
	s_mov_b32 s27, 0x7c000
	s_nop 0
	v_addc_co_u32_e32 v21, vcc, 0, v7, vcc
	global_load_dword v39, v[20:21], off nt
	v_add_co_u32_e32 v20, vcc, s43, v6
	s_nop 1
	v_addc_co_u32_e32 v21, vcc, 0, v7, vcc
	v_add_co_u32_e32 v6, vcc, s27, v6
	global_load_dword v20, v[20:21], off nt
	s_nop 0
	v_addc_co_u32_e32 v7, vcc, 0, v7, vcc
	global_load_dword v6, v[6:7], off nt
	v_add_u32_e32 v7, v42, v44
	s_waitcnt vmcnt(0)
	ds_write2_b32 v7, v8, v10 offset1:66
	ds_write2_b32 v7, v12, v14 offset0:132 offset1:198
	v_add_u32_e32 v8, 0x400, v7
	ds_write2_b32 v8, v9, v11 offset0:8 offset1:74
	ds_write2_b32 v8, v13, v18 offset0:140 offset1:206
	v_add_u32_e32 v8, 0x800, v7
	ds_write2_b32 v8, v15, v16 offset0:16 offset1:82
	ds_write2_b32 v8, v17, v22 offset0:148 offset1:214
	v_add_u32_e32 v8, 0xc00, v7
	ds_write2_b32 v8, v19, v23 offset0:24 offset1:90
	ds_write2_b32 v8, v24, v25 offset0:156 offset1:222
	v_add_u32_e32 v8, 0x1000, v7
	ds_write2_b32 v8, v26, v27 offset0:32 offset1:98
	ds_write2_b32 v8, v28, v29 offset0:164 offset1:230
	v_add_u32_e32 v8, 0x1400, v7
	ds_write2_b32 v8, v30, v31 offset0:40 offset1:106
	ds_write2_b32 v8, v32, v33 offset0:172 offset1:238
	v_add_u32_e32 v8, 0x1800, v7
	v_add_u32_e32 v7, 0x1c00, v7
	ds_write2_b32 v8, v34, v35 offset0:48 offset1:114
	ds_write2_b32 v8, v36, v37 offset0:180 offset1:246
	ds_write2_b32 v7, v38, v39 offset0:56 offset1:122
	ds_write2_b32 v7, v20, v6 offset0:188 offset1:254
	s_waitcnt lgkmcnt(0)
	ds_read2_b32 v[8:9], v43 offset1:33
	s_waitcnt lgkmcnt(0)
	v_cvt_pk_bf16_f32 v8, v8, v9
	ds_read2_b32 v[10:11], v43 offset0:66 offset1:99
	s_waitcnt lgkmcnt(0)
	v_cvt_pk_bf16_f32 v9, v10, v11
	ds_read2_b32 v[10:11], v43 offset0:132 offset1:165
	s_waitcnt lgkmcnt(0)
	v_cvt_pk_bf16_f32 v10, v10, v11
	ds_read2_b32 v[12:13], v43 offset0:198 offset1:231
	s_waitcnt lgkmcnt(0)
	v_cvt_pk_bf16_f32 v11, v12, v13
	v_add_u32_e32 v12, s26, v49
	v_ashrrev_i32_e32 v13, 31, v12
	v_lshl_add_u64 v[6:7], s[28:29], 1, v[2:3]
	v_lshlrev_b64 v[12:13], 12, v[12:13]
	v_lshl_add_u64 v[12:13], v[6:7], 0, v[12:13]
	global_store_dwordx4 v[12:13], v[8:11], off
	ds_read2_b32 v[8:9], v50 offset1:33
	s_waitcnt lgkmcnt(0)
	v_cvt_pk_bf16_f32 v8, v8, v9
	ds_read2_b32 v[10:11], v50 offset0:66 offset1:99
	s_waitcnt lgkmcnt(0)
	v_cvt_pk_bf16_f32 v9, v10, v11
	ds_read2_b32 v[10:11], v50 offset0:132 offset1:165
	s_waitcnt lgkmcnt(0)
	v_cvt_pk_bf16_f32 v10, v10, v11
	ds_read2_b32 v[12:13], v50 offset0:198 offset1:231
	s_waitcnt lgkmcnt(0)
	v_cvt_pk_bf16_f32 v11, v12, v13
	v_add_u32_e32 v12, s26, v45
	v_ashrrev_i32_e32 v13, 31, v12
	v_lshlrev_b64 v[12:13], 12, v[12:13]
	v_lshl_add_u64 v[12:13], v[6:7], 0, v[12:13]
	global_store_dwordx4 v[12:13], v[8:11], off
	ds_read2_b32 v[8:9], v51 offset1:33
	s_waitcnt lgkmcnt(0)
	v_cvt_pk_bf16_f32 v8, v8, v9
	ds_read2_b32 v[10:11], v51 offset0:66 offset1:99
	s_waitcnt lgkmcnt(0)
	v_cvt_pk_bf16_f32 v9, v10, v11
	ds_read2_b32 v[10:11], v51 offset0:132 offset1:165
	s_waitcnt lgkmcnt(0)
	v_cvt_pk_bf16_f32 v10, v10, v11
	ds_read2_b32 v[12:13], v51 offset0:198 offset1:231
	s_waitcnt lgkmcnt(0)
	v_cvt_pk_bf16_f32 v11, v12, v13
	v_add_u32_e32 v12, s26, v46
	v_ashrrev_i32_e32 v13, 31, v12
	v_lshlrev_b64 v[12:13], 12, v[12:13]
	v_lshl_add_u64 v[12:13], v[6:7], 0, v[12:13]
	global_store_dwordx4 v[12:13], v[8:11], off
	ds_read2_b32 v[8:9], v52 offset1:33
	s_waitcnt lgkmcnt(0)
	v_cvt_pk_bf16_f32 v8, v8, v9
	ds_read2_b32 v[10:11], v52 offset0:66 offset1:99
	s_waitcnt lgkmcnt(0)
	v_cvt_pk_bf16_f32 v9, v10, v11
	ds_read2_b32 v[10:11], v52 offset0:132 offset1:165
	s_waitcnt lgkmcnt(0)
	v_cvt_pk_bf16_f32 v10, v10, v11
	ds_read2_b32 v[12:13], v52 offset0:198 offset1:231
	s_waitcnt lgkmcnt(0)
	v_cvt_pk_bf16_f32 v11, v12, v13
	v_add_u32_e32 v12, s26, v47
	v_ashrrev_i32_e32 v13, 31, v12
	v_lshlrev_b64 v[12:13], 12, v[12:13]
	v_lshl_add_u64 v[6:7], v[6:7], 0, v[12:13]
	global_store_dwordx4 v[6:7], v[8:11], off
	s_waitcnt lgkmcnt(0)
	s_cbranch_scc1 .LBB0_569
	s_branch .LBB0_561
